# v87 + SwiGLU epilogue: gate*nml and e*var+var as packed ops with op_sel broadcast (64 fewer VALU per tile-wave)
# speedup vs baseline: 1.0084x; 1.0084x over previous
; __device__ __forceinline__ unsigned cvtpk(float lo, float hi) { f32x2 v = {lo, hi}; bf16x2_t b = __builtin_convertvector(v, bf16x2_t); return __builtin_bit_cast(unsigned, b); }
; __device__ __forceinline__ void load_rstd(const float* ssq, int row0, int fq, float (&rs)[2][4]) {
; #pragma unroll
;     for (int ai = 0; ai < 2; ++ai)
; #pragma unroll
;         for (int m = 0; m < 4; ++m) {
;             const f32x4 v = *(const f32x4*)(ssq + (size_t)(row0 + ai * HALF + m * 16) * 16 + 4 * fq);
;             float s = (v[0] + v[1]) + (v[2] + v[3]);
;             s += shx<16>(s); s += shx<32>(s);
;             rs[ai][m] = rsqrtf(s * (1.0f / 1024.0f) + RMS_EPS_F);
;         }
;     __device__ __forceinline__ void operator()(const f32x4 (&acc)[2][2][4][2], const Unit& u, int wr, int wc, int fr, int fq) const {
;         const int row0 = u.pm * BM + wr * 64 + fr;
;         const int col0 = 128 * u.pn + 32 * wc + 8 * fq;
;         float rs[2][4]; load_rstd(ssq, row0, fq, rs);
; #pragma unroll
;         for (int ai = 0; ai < 2; ++ai)
; #pragma unroll
;             for (int m = 0; m < 4; ++m) {
;                 const float mul = rs[ai][m], nml = -mul * LOG2E_F, mul2 = mul * mul;
;                 float hv[8];
; #pragma unroll
;                 for (int n = 0; n < 2; ++n)
; #pragma unroll
;                     for (int i = 0; i < 4; ++i) {
;                         const float ag = acc[ai][0][m][n][i];
;                         const float e = __builtin_amdgcn_exp2f(ag * nml);
;                         hv[4 * n + i] = (ag * acc[ai][1][m][n][i]) * (mul2 * __builtin_amdgcn_rcpf(1.0f + e));
;                     }
;                 u32x4 w; w.x = cvtpk(hv[0], hv[1]); w.y = cvtpk(hv[2], hv[3]); w.z = cvtpk(hv[4], hv[5]); w.w = cvtpk(hv[6], hv[7]);
;                 *(u32x4*)(H + (size_t)(row0 + ai * HALF + m * 16) * 2816 + col0) = w;
.LBB0_408:
	v_lshl_add_u32 v144, s6, 8, v3
	v_lshlrev_b32_e32 v146, 6, v144
	v_mov_b32_e32 v147, v2
	v_lshl_add_u64 v[148:149], v[138:139], 0, v[146:147]
	s_mov_b32 s100, 0x2000
	s_mov_b32 s101, 0
	v_lshl_add_u64 v[150:151], v[148:149], 0, s[100:101]
	global_load_dwordx4 v[168:171], v[148:149], off
	global_load_dwordx4 v[172:175], v[148:149], off offset:1024
	global_load_dwordx4 v[176:179], v[148:149], off offset:2048
	global_load_dwordx4 v[180:183], v[148:149], off offset:3072
	global_load_dwordx4 v[184:187], v[150:151], off
	global_load_dwordx4 v[188:191], v[150:151], off offset:1024
	global_load_dwordx4 v[192:195], v[150:151], off offset:2048
	global_load_dwordx4 v[202:205], v[150:151], off offset:3072
	v_mov_b64_e32 v[146:147], s[12:13]
	v_lshl_or_b32 v145, s3, 7, v165
	v_mad_i64_i32 v[226:227], s[6:7], v144, s88, v[146:147]
	v_lshlrev_b32_e32 v228, 1, v145
	v_mov_b32_e32 v229, v2
	v_lshl_add_u64 v[226:227], v[226:227], 0, v[228:229]
	v_mov_b32_e32 v147, 0x358637bd
	v_pk_mul_f32 v[124:125], v[128:129], v[124:125]
	v_pk_mul_f32 v[126:127], v[130:131], v[126:127]
	v_pk_mul_f32 v[116:117], v[120:121], v[116:117]
	v_pk_mul_f32 v[118:119], v[122:123], v[118:119]
	v_pk_mul_f32 v[108:109], v[112:113], v[108:109]
	v_pk_mul_f32 v[110:111], v[114:115], v[110:111]
	v_pk_mul_f32 v[100:101], v[104:105], v[100:101]
	v_pk_mul_f32 v[102:103], v[106:107], v[102:103]
	v_pk_mul_f32 v[92:93], v[96:97], v[92:93]
	v_pk_mul_f32 v[94:95], v[98:99], v[94:95]
	v_pk_mul_f32 v[84:85], v[88:89], v[84:85]
	v_pk_mul_f32 v[86:87], v[90:91], v[86:87]
	v_pk_mul_f32 v[76:77], v[80:81], v[76:77]
	v_pk_mul_f32 v[78:79], v[82:83], v[78:79]
	v_pk_mul_f32 v[68:69], v[72:73], v[68:69]
	v_pk_mul_f32 v[70:71], v[74:75], v[70:71]
	v_pk_mul_f32 v[60:61], v[64:65], v[60:61]
	v_pk_mul_f32 v[62:63], v[66:67], v[62:63]
	v_pk_mul_f32 v[52:53], v[56:57], v[52:53]
	v_pk_mul_f32 v[54:55], v[58:59], v[54:55]
	v_pk_mul_f32 v[44:45], v[48:49], v[44:45]
	v_pk_mul_f32 v[46:47], v[50:51], v[46:47]
	v_pk_mul_f32 v[36:37], v[40:41], v[36:37]
	v_pk_mul_f32 v[38:39], v[42:43], v[38:39]
	v_pk_mul_f32 v[28:29], v[32:33], v[28:29]
	v_pk_mul_f32 v[30:31], v[34:35], v[30:31]
	v_pk_mul_f32 v[20:21], v[24:25], v[20:21]
	v_pk_mul_f32 v[22:23], v[26:27], v[22:23]
	v_pk_mul_f32 v[12:13], v[16:17], v[12:13]
	v_pk_mul_f32 v[14:15], v[18:19], v[14:15]
	v_pk_mul_f32 v[4:5], v[8:9], v[4:5]
	v_pk_mul_f32 v[6:7], v[10:11], v[6:7]
	s_waitcnt vmcnt(7)
	v_add_f32_e32 v152, v168, v169
	v_add_f32_e32 v170, v170, v171
	v_add_f32_e32 v152, v152, v170
	s_waitcnt vmcnt(6)
	v_add_f32_e32 v153, v172, v173
	v_add_f32_e32 v174, v174, v175
	v_add_f32_e32 v153, v153, v174
	s_waitcnt vmcnt(5)
	v_add_f32_e32 v154, v176, v177
	v_add_f32_e32 v178, v178, v179
	v_add_f32_e32 v154, v154, v178
	s_waitcnt vmcnt(4)
	v_add_f32_e32 v155, v180, v181
	v_add_f32_e32 v182, v182, v183
	v_add_f32_e32 v155, v155, v182
	s_waitcnt vmcnt(3)
	v_add_f32_e32 v156, v184, v185
	v_add_f32_e32 v186, v186, v187
	v_add_f32_e32 v156, v156, v186
	s_waitcnt vmcnt(2)
	v_add_f32_e32 v157, v188, v189
	v_add_f32_e32 v190, v190, v191
	v_add_f32_e32 v157, v157, v190
	s_waitcnt vmcnt(1)
	v_add_f32_e32 v158, v192, v193
	v_add_f32_e32 v194, v194, v195
	v_add_f32_e32 v158, v158, v194
	s_waitcnt vmcnt(0)
	v_add_f32_e32 v159, v202, v203
	v_add_f32_e32 v204, v204, v205
	v_add_f32_e32 v159, v159, v204
	s_nop 1
	v_permlane32_swap_b32_e32 v152, v153
	v_permlane32_swap_b32_e32 v154, v155
	v_permlane32_swap_b32_e32 v156, v157
	v_permlane32_swap_b32_e32 v158, v159
	v_add_f32_e32 v152, v152, v153
	v_add_f32_e32 v154, v154, v155
	v_add_f32_e32 v156, v156, v157
	v_add_f32_e32 v158, v158, v159
	s_nop 1
	v_permlane16_swap_b32_e32 v152, v154
	v_permlane16_swap_b32_e32 v156, v158
	v_add_f32_e32 v152, v152, v154
	v_add_f32_e32 v156, v156, v158
	v_fmamk_f32 v160, v152, 0x3a800000, v147
	v_fmamk_f32 v161, v156, 0x3a800000, v147
	v_rsq_f32_e32 v162, v160
	v_rsq_f32_e32 v163, v161
	s_nop 0
	v_mul_f32_e32 v162, 0xbfb8aa3b, v162
	v_mul_f32_e32 v163, 0xbfb8aa3b, v163
	v_mov_b32_e32 v146, v160
	s_nop 1
	v_permlane16_swap_b32_e32 v160, v146
	v_mov_b32_e32 v202, v160
	v_mov_b32_e32 v204, v146
	v_mov_b32_e32 v203, v160
	v_mov_b32_e32 v205, v146
	s_nop 1
	v_permlane32_swap_b32_e32 v202, v203
	v_permlane32_swap_b32_e32 v204, v205
	v_mov_b32_e32 v146, v161
	s_nop 1
	v_permlane16_swap_b32_e32 v161, v146
	v_mov_b32_e32 v206, v161
	v_mov_b32_e32 v208, v146
	v_mov_b32_e32 v207, v161
	v_mov_b32_e32 v209, v146
	s_nop 1
	v_permlane32_swap_b32_e32 v206, v207
	v_permlane32_swap_b32_e32 v208, v209
	v_mov_b32_e32 v146, v162
	s_nop 1
	v_permlane16_swap_b32_e32 v162, v146
	v_mov_b32_e32 v210, v162
	v_mov_b32_e32 v212, v146
	v_mov_b32_e32 v211, v162
	v_mov_b32_e32 v213, v146
	s_nop 1
	v_permlane32_swap_b32_e32 v210, v211
	v_permlane32_swap_b32_e32 v212, v213
	v_mov_b32_e32 v146, v163
	s_nop 1
	v_permlane16_swap_b32_e32 v163, v146
	v_mov_b32_e32 v214, v163
	v_mov_b32_e32 v216, v146
	v_mov_b32_e32 v215, v163
	v_mov_b32_e32 v217, v146
	s_nop 1
	v_permlane32_swap_b32_e32 v214, v215
	v_permlane32_swap_b32_e32 v216, v217
	v_pk_mul_f32 v[218:219], v[128:129], v[210:211] op_sel_hi:[1,0]
	v_pk_mul_f32 v[220:221], v[130:131], v[210:211] op_sel_hi:[1,0]
	v_pk_mul_f32 v[222:223], v[120:121], v[210:211] op_sel_hi:[1,0]
	v_pk_mul_f32 v[224:225], v[122:123], v[210:211] op_sel_hi:[1,0]
	v_exp_f32_e32 v218, v218
	v_exp_f32_e32 v219, v219
	v_exp_f32_e32 v220, v220
	v_exp_f32_e32 v221, v221
	v_exp_f32_e32 v222, v222
	v_exp_f32_e32 v223, v223
	v_exp_f32_e32 v224, v224
	v_exp_f32_e32 v225, v225
	s_mov_b32 s100, 0x0
	v_lshl_add_u64 v[228:229], v[226:227], 0, s[100:101]
	v_pk_fma_f32 v[218:219], v[218:219], v[202:203], v[202:203] op_sel_hi:[1,0,0]
; __device__ __forceinline__ unsigned cvtpk(float lo, float hi) { f32x2 v = {lo, hi}; bf16x2_t b = __builtin_convertvector(v, bf16x2_t); return __builtin_bit_cast(unsigned, b); }
;     __device__ __forceinline__ void operator()(const f32x4 (&acc)[2][2][4][2], const Unit& u, int wr, int wc, int fr, int fq) const {
;     ...
;             for (int m = 0; m < 4; ++m) {
;                 const float mul = rs[ai][m], nml = -mul * LOG2E_F, mul2 = mul * mul;
;                 float hv[8];
; #pragma unroll
;                 for (int n = 0; n < 2; ++n)
; #pragma unroll
;                     for (int i = 0; i < 4; ++i) {
;                         const float ag = acc[ai][0][m][n][i];
;                         const float e = __builtin_amdgcn_exp2f(ag * nml);
;                         hv[4 * n + i] = (ag * acc[ai][1][m][n][i]) * (mul2 * __builtin_amdgcn_rcpf(1.0f + e));
;                     }
;                 u32x4 w; w.x = cvtpk(hv[0], hv[1]); w.y = cvtpk(hv[2], hv[3]); w.z = cvtpk(hv[4], hv[5]); w.w = cvtpk(hv[6], hv[7]);
;                 *(u32x4*)(H + (size_t)(row0 + ai * HALF + m * 16) * 2816 + col0) = w;
	v_pk_fma_f32 v[220:221], v[220:221], v[202:203], v[202:203] op_sel_hi:[1,0,0]
	v_pk_fma_f32 v[222:223], v[222:223], v[202:203], v[202:203] op_sel_hi:[1,0,0]
	v_pk_fma_f32 v[224:225], v[224:225], v[202:203], v[202:203] op_sel_hi:[1,0,0]
	v_rcp_f32_e32 v218, v218
	v_rcp_f32_e32 v219, v219
	v_rcp_f32_e32 v220, v220
	v_rcp_f32_e32 v221, v221
	v_rcp_f32_e32 v222, v222
	v_rcp_f32_e32 v223, v223
	v_rcp_f32_e32 v224, v224
	v_rcp_f32_e32 v225, v225
	s_nop 0
	v_pk_mul_f32 v[124:125], v[124:125], v[218:219]
	v_pk_mul_f32 v[126:127], v[126:127], v[220:221]
	v_pk_mul_f32 v[116:117], v[116:117], v[222:223]
	v_pk_mul_f32 v[118:119], v[118:119], v[224:225]
	v_cvt_pk_bf16_f32 v120, v124, v125
	v_cvt_pk_bf16_f32 v121, v126, v127
	v_cvt_pk_bf16_f32 v122, v116, v117
	v_cvt_pk_bf16_f32 v123, v118, v119
	global_store_dwordx4 v[228:229], v[120:123], off
	v_pk_mul_f32 v[218:219], v[112:113], v[210:211] op_sel:[0,1] op_sel_hi:[1,1]
	v_pk_mul_f32 v[220:221], v[114:115], v[210:211] op_sel:[0,1] op_sel_hi:[1,1]
	v_pk_mul_f32 v[222:223], v[104:105], v[210:211] op_sel:[0,1] op_sel_hi:[1,1]
	v_pk_mul_f32 v[224:225], v[106:107], v[210:211] op_sel:[0,1] op_sel_hi:[1,1]
	v_exp_f32_e32 v218, v218
	v_exp_f32_e32 v219, v219
	v_exp_f32_e32 v220, v220
	v_exp_f32_e32 v221, v221
	v_exp_f32_e32 v222, v222
	v_exp_f32_e32 v223, v223
	v_exp_f32_e32 v224, v224
	v_exp_f32_e32 v225, v225
	s_mov_b32 s100, 0x16000
	v_lshl_add_u64 v[228:229], v[226:227], 0, s[100:101]
	v_pk_fma_f32 v[218:219], v[218:219], v[202:203], v[202:203] op_sel:[0,1,1] op_sel_hi:[1,1,1]
	v_pk_fma_f32 v[220:221], v[220:221], v[202:203], v[202:203] op_sel:[0,1,1] op_sel_hi:[1,1,1]
	v_pk_fma_f32 v[222:223], v[222:223], v[202:203], v[202:203] op_sel:[0,1,1] op_sel_hi:[1,1,1]
	v_pk_fma_f32 v[224:225], v[224:225], v[202:203], v[202:203] op_sel:[0,1,1] op_sel_hi:[1,1,1]
	v_rcp_f32_e32 v218, v218
	v_rcp_f32_e32 v219, v219
	v_rcp_f32_e32 v220, v220
	v_rcp_f32_e32 v221, v221
	v_rcp_f32_e32 v222, v222
	v_rcp_f32_e32 v223, v223
	v_rcp_f32_e32 v224, v224
	v_rcp_f32_e32 v225, v225
	s_nop 0
	v_pk_mul_f32 v[108:109], v[108:109], v[218:219]
	v_pk_mul_f32 v[110:111], v[110:111], v[220:221]
	v_pk_mul_f32 v[100:101], v[100:101], v[222:223]
	v_pk_mul_f32 v[102:103], v[102:103], v[224:225]
	v_cvt_pk_bf16_f32 v104, v108, v109
	v_cvt_pk_bf16_f32 v105, v110, v111
	v_cvt_pk_bf16_f32 v106, v100, v101
	v_cvt_pk_bf16_f32 v107, v102, v103
	global_store_dwordx4 v[228:229], v[104:107], off
	v_pk_mul_f32 v[218:219], v[96:97], v[212:213] op_sel_hi:[1,0]
	v_pk_mul_f32 v[220:221], v[98:99], v[212:213] op_sel_hi:[1,0]
	v_pk_mul_f32 v[222:223], v[88:89], v[212:213] op_sel_hi:[1,0]
	v_pk_mul_f32 v[224:225], v[90:91], v[212:213] op_sel_hi:[1,0]
	v_exp_f32_e32 v218, v218
	v_exp_f32_e32 v219, v219
	v_exp_f32_e32 v220, v220
	v_exp_f32_e32 v221, v221
	v_exp_f32_e32 v222, v222
	v_exp_f32_e32 v223, v223
	v_exp_f32_e32 v224, v224
	v_exp_f32_e32 v225, v225
	s_mov_b32 s100, 0x2c000
	v_lshl_add_u64 v[228:229], v[226:227], 0, s[100:101]
	v_pk_fma_f32 v[218:219], v[218:219], v[204:205], v[204:205] op_sel_hi:[1,0,0]
	v_pk_fma_f32 v[220:221], v[220:221], v[204:205], v[204:205] op_sel_hi:[1,0,0]
	v_pk_fma_f32 v[222:223], v[222:223], v[204:205], v[204:205] op_sel_hi:[1,0,0]
	v_pk_fma_f32 v[224:225], v[224:225], v[204:205], v[204:205] op_sel_hi:[1,0,0]
	v_rcp_f32_e32 v218, v218
	v_rcp_f32_e32 v219, v219
	v_rcp_f32_e32 v220, v220
	v_rcp_f32_e32 v221, v221
	v_rcp_f32_e32 v222, v222
	v_rcp_f32_e32 v223, v223
	v_rcp_f32_e32 v224, v224
	v_rcp_f32_e32 v225, v225
	s_nop 0
	v_pk_mul_f32 v[92:93], v[92:93], v[218:219]
	v_pk_mul_f32 v[94:95], v[94:95], v[220:221]
	v_pk_mul_f32 v[84:85], v[84:85], v[222:223]
	v_pk_mul_f32 v[86:87], v[86:87], v[224:225]
	v_cvt_pk_bf16_f32 v88, v92, v93
	v_cvt_pk_bf16_f32 v89, v94, v95
	v_cvt_pk_bf16_f32 v90, v84, v85
	v_cvt_pk_bf16_f32 v91, v86, v87
	global_store_dwordx4 v[228:229], v[88:91], off
	v_pk_mul_f32 v[218:219], v[80:81], v[212:213] op_sel:[0,1] op_sel_hi:[1,1]
	v_pk_mul_f32 v[220:221], v[82:83], v[212:213] op_sel:[0,1] op_sel_hi:[1,1]
	v_pk_mul_f32 v[222:223], v[72:73], v[212:213] op_sel:[0,1] op_sel_hi:[1,1]
	v_pk_mul_f32 v[224:225], v[74:75], v[212:213] op_sel:[0,1] op_sel_hi:[1,1]
	v_exp_f32_e32 v218, v218
	v_exp_f32_e32 v219, v219
	v_exp_f32_e32 v220, v220
	v_exp_f32_e32 v221, v221
	v_exp_f32_e32 v222, v222
	v_exp_f32_e32 v223, v223
	v_exp_f32_e32 v224, v224
	v_exp_f32_e32 v225, v225
	s_mov_b32 s100, 0x42000
	v_lshl_add_u64 v[228:229], v[226:227], 0, s[100:101]
	v_pk_fma_f32 v[218:219], v[218:219], v[204:205], v[204:205] op_sel:[0,1,1] op_sel_hi:[1,1,1]
	v_pk_fma_f32 v[220:221], v[220:221], v[204:205], v[204:205] op_sel:[0,1,1] op_sel_hi:[1,1,1]
	v_pk_fma_f32 v[222:223], v[222:223], v[204:205], v[204:205] op_sel:[0,1,1] op_sel_hi:[1,1,1]
	v_pk_fma_f32 v[224:225], v[224:225], v[204:205], v[204:205] op_sel:[0,1,1] op_sel_hi:[1,1,1]
	v_rcp_f32_e32 v218, v218
	v_rcp_f32_e32 v219, v219
	v_rcp_f32_e32 v220, v220
	v_rcp_f32_e32 v221, v221
	v_rcp_f32_e32 v222, v222
	v_rcp_f32_e32 v223, v223
	v_rcp_f32_e32 v224, v224
	v_rcp_f32_e32 v225, v225
	s_nop 0
	v_pk_mul_f32 v[76:77], v[76:77], v[218:219]
	v_pk_mul_f32 v[78:79], v[78:79], v[220:221]
	v_pk_mul_f32 v[68:69], v[68:69], v[222:223]
	v_pk_mul_f32 v[70:71], v[70:71], v[224:225]
	v_cvt_pk_bf16_f32 v72, v76, v77
	v_cvt_pk_bf16_f32 v73, v78, v79
	v_cvt_pk_bf16_f32 v74, v68, v69
	v_cvt_pk_bf16_f32 v75, v70, v71
	global_store_dwordx4 v[228:229], v[72:75], off
	v_pk_mul_f32 v[218:219], v[64:65], v[214:215] op_sel_hi:[1,0]
	v_pk_mul_f32 v[220:221], v[66:67], v[214:215] op_sel_hi:[1,0]
	v_pk_mul_f32 v[222:223], v[56:57], v[214:215] op_sel_hi:[1,0]
	v_pk_mul_f32 v[224:225], v[58:59], v[214:215] op_sel_hi:[1,0]
; __device__ __forceinline__ unsigned cvtpk(float lo, float hi) { f32x2 v = {lo, hi}; bf16x2_t b = __builtin_convertvector(v, bf16x2_t); return __builtin_bit_cast(unsigned, b); }
; #define PG8_BAR __builtin_amdgcn_s_barrier()
;     __device__ __forceinline__ void operator()(const f32x4 (&acc)[2][2][4][2], const Unit& u, int wr, int wc, int fr, int fq) const {
;     ...
;             for (int m = 0; m < 4; ++m) {
;                 const float mul = rs[ai][m], nml = -mul * LOG2E_F, mul2 = mul * mul;
;                 float hv[8];
; #pragma unroll
;                 for (int n = 0; n < 2; ++n)
; #pragma unroll
;                     for (int i = 0; i < 4; ++i) {
;                         const float ag = acc[ai][0][m][n][i];
;                         const float e = __builtin_amdgcn_exp2f(ag * nml);
;                         hv[4 * n + i] = (ag * acc[ai][1][m][n][i]) * (mul2 * __builtin_amdgcn_rcpf(1.0f + e));
;                     }
;                 u32x4 w; w.x = cvtpk(hv[0], hv[1]); w.y = cvtpk(hv[2], hv[3]); w.z = cvtpk(hv[4], hv[5]); w.w = cvtpk(hv[6], hv[7]);
;                 *(u32x4*)(H + (size_t)(row0 + ai * HALF + m * 16) * 2816 + col0) = w;
; template <class Epi, class Sched, bool ALIGN_EPI = false, bool SP2 = false>
; __device__ __forceinline__ void gemm_phase(PG8_LAS unsigned char* lds, const Gemm g, const Sched& S, const Epi& E) {
;     ...
;         if constexpr (ALIGN_EPI) { if (wr == 0) PG8_BAR; }
;         if constexpr (!Epi::AFTER_DRAIN) { E(acc, cur, wr, wc, fr, fq); S.done(cur); }
;         if (!has_next) break;
; #pragma unroll
;         for (int a = 0; a < 2; ++a)
; #pragma unroll
;             for (int b = 0; b < 2; ++b)
; #pragma unroll
;                 for (int m = 0; m < 4; ++m)
; #pragma unroll
;                     for (int n = 0; n < 2; ++n) acc[a][b][m][n] = (f32x4){0.f, 0.f, 0.f, 0.f};
;         cur = nxt; cA = nA; cB = nB; ++ui;
;         if constexpr (ALIGN_EPI) { if (wr == 1) PG8_BAR; }
	v_exp_f32_e32 v218, v218
	v_exp_f32_e32 v219, v219
	v_exp_f32_e32 v220, v220
	v_exp_f32_e32 v221, v221
	v_exp_f32_e32 v222, v222
	v_exp_f32_e32 v223, v223
	v_exp_f32_e32 v224, v224
	v_exp_f32_e32 v225, v225
	s_mov_b32 s100, 0xb0000
	v_lshl_add_u64 v[228:229], v[226:227], 0, s[100:101]
	v_pk_fma_f32 v[218:219], v[218:219], v[206:207], v[206:207] op_sel_hi:[1,0,0]
	v_pk_fma_f32 v[220:221], v[220:221], v[206:207], v[206:207] op_sel_hi:[1,0,0]
	v_pk_fma_f32 v[222:223], v[222:223], v[206:207], v[206:207] op_sel_hi:[1,0,0]
	v_pk_fma_f32 v[224:225], v[224:225], v[206:207], v[206:207] op_sel_hi:[1,0,0]
	v_rcp_f32_e32 v218, v218
	v_rcp_f32_e32 v219, v219
	v_rcp_f32_e32 v220, v220
	v_rcp_f32_e32 v221, v221
	v_rcp_f32_e32 v222, v222
	v_rcp_f32_e32 v223, v223
	v_rcp_f32_e32 v224, v224
	v_rcp_f32_e32 v225, v225
	s_nop 0
	v_pk_mul_f32 v[60:61], v[60:61], v[218:219]
	v_pk_mul_f32 v[62:63], v[62:63], v[220:221]
	v_pk_mul_f32 v[52:53], v[52:53], v[222:223]
	v_pk_mul_f32 v[54:55], v[54:55], v[224:225]
	v_cvt_pk_bf16_f32 v56, v60, v61
	v_cvt_pk_bf16_f32 v57, v62, v63
	v_cvt_pk_bf16_f32 v58, v52, v53
	v_cvt_pk_bf16_f32 v59, v54, v55
	global_store_dwordx4 v[228:229], v[56:59], off
	v_pk_mul_f32 v[218:219], v[48:49], v[214:215] op_sel:[0,1] op_sel_hi:[1,1]
	v_pk_mul_f32 v[220:221], v[50:51], v[214:215] op_sel:[0,1] op_sel_hi:[1,1]
	v_pk_mul_f32 v[222:223], v[40:41], v[214:215] op_sel:[0,1] op_sel_hi:[1,1]
	v_pk_mul_f32 v[224:225], v[42:43], v[214:215] op_sel:[0,1] op_sel_hi:[1,1]
	v_exp_f32_e32 v218, v218
	v_exp_f32_e32 v219, v219
	v_exp_f32_e32 v220, v220
	v_exp_f32_e32 v221, v221
	v_exp_f32_e32 v222, v222
	v_exp_f32_e32 v223, v223
	v_exp_f32_e32 v224, v224
	v_exp_f32_e32 v225, v225
	s_mov_b32 s100, 0xc6000
	v_lshl_add_u64 v[228:229], v[226:227], 0, s[100:101]
	v_pk_fma_f32 v[218:219], v[218:219], v[206:207], v[206:207] op_sel:[0,1,1] op_sel_hi:[1,1,1]
	v_pk_fma_f32 v[220:221], v[220:221], v[206:207], v[206:207] op_sel:[0,1,1] op_sel_hi:[1,1,1]
	v_pk_fma_f32 v[222:223], v[222:223], v[206:207], v[206:207] op_sel:[0,1,1] op_sel_hi:[1,1,1]
	v_pk_fma_f32 v[224:225], v[224:225], v[206:207], v[206:207] op_sel:[0,1,1] op_sel_hi:[1,1,1]
	v_rcp_f32_e32 v218, v218
	v_rcp_f32_e32 v219, v219
	v_rcp_f32_e32 v220, v220
	v_rcp_f32_e32 v221, v221
	v_rcp_f32_e32 v222, v222
	v_rcp_f32_e32 v223, v223
	v_rcp_f32_e32 v224, v224
	v_rcp_f32_e32 v225, v225
	s_nop 0
	v_pk_mul_f32 v[44:45], v[44:45], v[218:219]
	v_pk_mul_f32 v[46:47], v[46:47], v[220:221]
	v_pk_mul_f32 v[36:37], v[36:37], v[222:223]
	v_pk_mul_f32 v[38:39], v[38:39], v[224:225]
	v_cvt_pk_bf16_f32 v40, v44, v45
	v_cvt_pk_bf16_f32 v41, v46, v47
	v_cvt_pk_bf16_f32 v42, v36, v37
	v_cvt_pk_bf16_f32 v43, v38, v39
	global_store_dwordx4 v[228:229], v[40:43], off
	v_pk_mul_f32 v[218:219], v[32:33], v[216:217] op_sel_hi:[1,0]
	v_pk_mul_f32 v[220:221], v[34:35], v[216:217] op_sel_hi:[1,0]
	v_pk_mul_f32 v[222:223], v[24:25], v[216:217] op_sel_hi:[1,0]
	v_pk_mul_f32 v[224:225], v[26:27], v[216:217] op_sel_hi:[1,0]
	v_exp_f32_e32 v218, v218
	v_exp_f32_e32 v219, v219
	v_exp_f32_e32 v220, v220
	v_exp_f32_e32 v221, v221
	v_exp_f32_e32 v222, v222
	v_exp_f32_e32 v223, v223
	v_exp_f32_e32 v224, v224
	v_exp_f32_e32 v225, v225
	s_mov_b32 s100, 0xdc000
	v_lshl_add_u64 v[228:229], v[226:227], 0, s[100:101]
	v_pk_fma_f32 v[218:219], v[218:219], v[208:209], v[208:209] op_sel_hi:[1,0,0]
	v_pk_fma_f32 v[220:221], v[220:221], v[208:209], v[208:209] op_sel_hi:[1,0,0]
	v_pk_fma_f32 v[222:223], v[222:223], v[208:209], v[208:209] op_sel_hi:[1,0,0]
	v_pk_fma_f32 v[224:225], v[224:225], v[208:209], v[208:209] op_sel_hi:[1,0,0]
	v_rcp_f32_e32 v218, v218
	v_rcp_f32_e32 v219, v219
	v_rcp_f32_e32 v220, v220
	v_rcp_f32_e32 v221, v221
	v_rcp_f32_e32 v222, v222
	v_rcp_f32_e32 v223, v223
	v_rcp_f32_e32 v224, v224
	v_rcp_f32_e32 v225, v225
	s_nop 0
	v_pk_mul_f32 v[28:29], v[28:29], v[218:219]
	v_pk_mul_f32 v[30:31], v[30:31], v[220:221]
	v_pk_mul_f32 v[20:21], v[20:21], v[222:223]
	v_pk_mul_f32 v[22:23], v[22:23], v[224:225]
	v_cvt_pk_bf16_f32 v24, v28, v29
	v_cvt_pk_bf16_f32 v25, v30, v31
	v_cvt_pk_bf16_f32 v26, v20, v21
	v_cvt_pk_bf16_f32 v27, v22, v23
	global_store_dwordx4 v[228:229], v[24:27], off
	v_pk_mul_f32 v[218:219], v[16:17], v[216:217] op_sel:[0,1] op_sel_hi:[1,1]
	v_pk_mul_f32 v[220:221], v[18:19], v[216:217] op_sel:[0,1] op_sel_hi:[1,1]
	v_pk_mul_f32 v[222:223], v[8:9], v[216:217] op_sel:[0,1] op_sel_hi:[1,1]
	v_pk_mul_f32 v[224:225], v[10:11], v[216:217] op_sel:[0,1] op_sel_hi:[1,1]
	v_exp_f32_e32 v218, v218
	v_exp_f32_e32 v219, v219
	v_exp_f32_e32 v220, v220
	v_exp_f32_e32 v221, v221
	v_exp_f32_e32 v222, v222
	v_exp_f32_e32 v223, v223
	v_exp_f32_e32 v224, v224
	v_exp_f32_e32 v225, v225
	s_mov_b32 s100, 0xf2000
	v_lshl_add_u64 v[228:229], v[226:227], 0, s[100:101]
	v_pk_fma_f32 v[218:219], v[218:219], v[208:209], v[208:209] op_sel:[0,1,1] op_sel_hi:[1,1,1]
	v_pk_fma_f32 v[220:221], v[220:221], v[208:209], v[208:209] op_sel:[0,1,1] op_sel_hi:[1,1,1]
	v_pk_fma_f32 v[222:223], v[222:223], v[208:209], v[208:209] op_sel:[0,1,1] op_sel_hi:[1,1,1]
	v_pk_fma_f32 v[224:225], v[224:225], v[208:209], v[208:209] op_sel:[0,1,1] op_sel_hi:[1,1,1]
	v_rcp_f32_e32 v218, v218
	v_rcp_f32_e32 v219, v219
	v_rcp_f32_e32 v220, v220
	v_rcp_f32_e32 v221, v221
	v_rcp_f32_e32 v222, v222
	v_rcp_f32_e32 v223, v223
	v_rcp_f32_e32 v224, v224
	v_rcp_f32_e32 v225, v225
	s_nop 0
	v_pk_mul_f32 v[12:13], v[12:13], v[218:219]
	v_pk_mul_f32 v[14:15], v[14:15], v[220:221]
	v_pk_mul_f32 v[4:5], v[4:5], v[222:223]
	v_pk_mul_f32 v[6:7], v[6:7], v[224:225]
	v_cvt_pk_bf16_f32 v8, v12, v13
	v_cvt_pk_bf16_f32 v9, v14, v15
	v_cvt_pk_bf16_f32 v10, v4, v5
	v_cvt_pk_bf16_f32 v11, v6, v7
	global_store_dwordx4 v[228:229], v[8:11], off
	s_andn2_b64 vcc, exec, s[4:5]
	s_mov_b64 s[4:5], -1
	s_cbranch_vccnz .LBB0_401
	s_andn2_b64 vcc, exec, s[10:11]
	s_cbranch_vccnz .LBB0_400
	s_barrier
	s_branch .LBB0_400
